# v026 + NSA attention loops: next-stage K/V global loads issued after the first tile's K reads are in flight (out of the post-barrier head); loop-top flags formed with s_cselect
# baseline (speedup 1.0000x reference)
; template <bool HAS_POST, class MaskF>
; __device__ __forceinline__ void attn_run(LAS unsigned char* lds, const bf16* Kg, const bf16* Vg, int pitch, int t0, int t1,
;                                          const bf16x8 (&qr)[4], f32x16& o0, f32x16& o1, f32x16& o2, MaskF& mf, const int wv) {
;     ...
;     for (int ts = t0; ts < t1; ts += 2) {
;         const int cur = ((ts - t0) >> 1) & 1;
;         const bool more = (ts + 2 < t1), more2 = (ts + 3 < t1);
;         if (more) { kp += 2 * tstride; kreg0 = *(const v4u*)kp; vp += 2 * tstride; vreg0 = *(const v4u*)vp;
;             if (more2) { kreg1 = *(const v4u*)(kp + tstride); vreg1 = *(const v4u*)(vp + tstride); } }
.LBB0_851:
	s_add_i32 s0, s16, -2
	s_cmp_lt_i32 s16, s34
	s_cselect_b64 s[14:15], -1, 0
	s_cmp_ge_i32 s16, s34
	s_cselect_b64 s[12:13], -1, 0
	s_cmp_lt_i32 s0, s22
	s_cselect_b64 s[4:5], -1, 0
	s_cselect_b64 s[6:7], 0, exec
	s_and_b64 vcc, exec, s[12:13]

; #define LAS __attribute__((address_space(3)))
;     __device__ __forceinline__ bool skip(int t) const { const int nb = t >> 2; if (nb >= qb) return 64 * (t & 3) > wq0 + 31; return !__any((int)((sel >> nb) & 1u)); }
; template <bool HAS_POST, class MaskF>
; __device__ __forceinline__ void attn_run(LAS unsigned char* lds, const bf16* Kg, const bf16* Vg, int pitch, int t0, int t1,
;                                          const bf16x8 (&qr)[4], f32x16& o0, f32x16& o1, f32x16& o2, MaskF& mf, const int wv) {
;     ...
;         if (more) { kp += 2 * tstride; kreg0 = *(const v4u*)kp; vp += 2 * tstride; vreg0 = *(const v4u*)vp;
;             if (more2) { kreg1 = *(const v4u*)(kp + tstride); vreg1 = *(const v4u*)(vp + tstride); } }
; #pragma unroll
;         for (int j = 0; j < 2; ++j) {
;             const int t = ts + j;
;             if (t >= t1) break;
;             if (mf.skip(t)) continue;
;             f32x16 p0, p1; const f32x16 zc = {};
;             LAS unsigned char* Kb = lds + (cur * 2 + j) * KBUF + cx.kroff;
;             if (wv < 4) __builtin_amdgcn_s_setprio(1);
; #pragma unroll
;             for (int d0 = 0; d0 < 4; ++d0) {
;                 const bf16x8 a0 = *(const LAS bf16x8*)(Kb + d0 * 32), a1 = *(const LAS bf16x8*)(Kb + 32 * 144 + d0 * 32);
;                 if (d0 == 0) { p0 = __builtin_amdgcn_mfma_f32_32x32x16_bf16(a0, qr[0], zc, 0, 0, 0); p1 = __builtin_amdgcn_mfma_f32_32x32x16_bf16(a1, qr[0], zc, 0, 0, 0); }
;                 else { p0 = __builtin_amdgcn_mfma_f32_32x32x16_bf16(a0, qr[d0], p0, 0, 0, 0); p1 = __builtin_amdgcn_mfma_f32_32x32x16_bf16(a1, qr[d0], p1, 0, 0, 0); }
.LBB0_858:
	s_mul_i32 s0, s18, 0x2400
	v_add_u32_e32 v106, s0, v167
	ds_read_b128 v[102:105], v106
	ds_read_b128 v[110:113], v106 offset:32
	ds_read_b128 v[50:53], v106 offset:4608
	ds_read_b128 v[132:135], v106 offset:4640
	ds_read_b128 v[136:139], v106 offset:64
	ds_read_b128 v[140:143], v106 offset:4672
	ds_read_b128 v[144:147], v106 offset:96
	ds_read_b128 v[148:151], v106 offset:4704
	s_and_b64 vcc, exec, s[12:13]
	s_cbranch_vccnz .Lnb_6
	s_mov_b64 s[98:99], 0x4000
	v_lshl_add_u64 v[154:155], v[154:155], 0, s[98:99]
	v_lshl_add_u64 v[156:157], v[156:157], 0, s[98:99]
	global_load_dwordx4 v[82:85], v[154:155], off
	global_load_dwordx4 v[86:89], v[156:157], off
	s_and_b64 vcc, exec, s[6:7]
	s_cbranch_vccnz .LBB0_854
	s_mov_b64 s[98:99], 0x2000
	v_lshl_add_u64 v[228:229], v[154:155], 0, s[98:99]
	global_load_dwordx4 v[90:93], v[228:229], off
	v_lshl_add_u64 v[228:229], v[156:157], 0, s[98:99]
	global_load_dwordx4 v[94:97], v[228:229], off
.LBB0_854:
.Lnb_6:
	s_and_b64 vcc, exec, s[8:9]
	s_waitcnt lgkmcnt(7)
	v_mfma_f32_32x32x16_bf16 v[66:81], v[102:105], v[116:119], 0
	s_waitcnt lgkmcnt(6)
	v_mfma_f32_32x32x16_bf16 v[66:81], v[110:113], v[120:123], v[66:81]
	s_waitcnt lgkmcnt(5)
	v_mfma_f32_32x32x16_bf16 v[50:65], v[50:53], v[116:119], 0
	s_waitcnt lgkmcnt(4)
	v_mfma_f32_32x32x16_bf16 v[50:65], v[132:135], v[120:123], v[50:65]
	s_waitcnt lgkmcnt(3)
	v_mfma_f32_32x32x16_bf16 v[66:81], v[136:139], v[124:127], v[66:81]
	s_waitcnt lgkmcnt(2)
	v_mfma_f32_32x32x16_bf16 v[50:65], v[140:143], v[124:127], v[50:65]
	s_waitcnt lgkmcnt(1)
	v_mfma_f32_32x32x16_bf16 v[66:81], v[144:147], v[128:131], v[66:81]
	s_waitcnt lgkmcnt(0)
	v_mfma_f32_32x32x16_bf16 v[50:65], v[148:151], v[128:131], v[50:65]
	s_cbranch_vccnz .LBB0_860
	s_setprio 0

; template <bool HAS_POST, class MaskF>
; __device__ __forceinline__ void attn_run(LAS unsigned char* lds, const bf16* Kg, const bf16* Vg, int pitch, int t0, int t1,
;                                          const bf16x8 (&qr)[4], f32x16& o0, f32x16& o1, f32x16& o2, MaskF& mf, const int wv) {
;     ...
;     for (int ts = t0; ts < t1; ts += 2) {
;         const int cur = ((ts - t0) >> 1) & 1;
;         const bool more = (ts + 2 < t1), more2 = (ts + 3 < t1);
;         if (more) { kp += 2 * tstride; kreg0 = *(const v4u*)kp; vp += 2 * tstride; vreg0 = *(const v4u*)vp;
;             if (more2) { kreg1 = *(const v4u*)(kp + tstride); vreg1 = *(const v4u*)(vp + tstride); } }
.LBB0_921:
	s_add_u32 s94, s4, 2
	s_addc_u32 s95, s5, 0
	s_cmp_gt_i32 s94, s38
	s_cselect_b64 s[20:21], -1, 0
	s_cmp_le_i32 s94, s38
	s_cselect_b64 s[96:97], -1, 0
	s_cmp_lt_i32 s4, s23
	s_cselect_b64 s[0:1], -1, 0
	s_cselect_b64 s[92:93], 0, exec
	s_and_b64 vcc, exec, s[20:21]

; #define LAS __attribute__((address_space(3)))
;     __device__ __forceinline__ bool skip(int t) const { const int nb = t >> 2; if (nb >= qb) return 64 * (t & 3) > wq0 + 31; return !__any((int)((sel >> nb) & 1u)); }
; template <bool HAS_POST, class MaskF>
; __device__ __forceinline__ void attn_run(LAS unsigned char* lds, const bf16* Kg, const bf16* Vg, int pitch, int t0, int t1,
;                                          const bf16x8 (&qr)[4], f32x16& o0, f32x16& o1, f32x16& o2, MaskF& mf, const int wv) {
;     ...
;         if (more) { kp += 2 * tstride; kreg0 = *(const v4u*)kp; vp += 2 * tstride; vreg0 = *(const v4u*)vp;
;             if (more2) { kreg1 = *(const v4u*)(kp + tstride); vreg1 = *(const v4u*)(vp + tstride); } }
; #pragma unroll
;         for (int j = 0; j < 2; ++j) {
;             const int t = ts + j;
;             if (t >= t1) break;
;             if (mf.skip(t)) continue;
;             f32x16 p0, p1; const f32x16 zc = {};
;             LAS unsigned char* Kb = lds + (cur * 2 + j) * KBUF + cx.kroff;
;             if (wv < 4) __builtin_amdgcn_s_setprio(1);
; #pragma unroll
;             for (int d0 = 0; d0 < 4; ++d0) {
;                 const bf16x8 a0 = *(const LAS bf16x8*)(Kb + d0 * 32), a1 = *(const LAS bf16x8*)(Kb + 32 * 144 + d0 * 32);
;                 if (d0 == 0) { p0 = __builtin_amdgcn_mfma_f32_32x32x16_bf16(a0, qr[0], zc, 0, 0, 0); p1 = __builtin_amdgcn_mfma_f32_32x32x16_bf16(a1, qr[0], zc, 0, 0, 0); }
;                 else { p0 = __builtin_amdgcn_mfma_f32_32x32x16_bf16(a0, qr[d0], p0, 0, 0, 0); p1 = __builtin_amdgcn_mfma_f32_32x32x16_bf16(a1, qr[d0], p1, 0, 0, 0); }
.LBB0_928:
	s_mul_i32 s0, s5, 0x2400
	v_add_u32_e32 v168, s0, v166
	ds_read_b128 v[50:53], v168
	ds_read_b128 v[102:105], v168 offset:32
	ds_read_b128 v[66:69], v168 offset:4608
	ds_read_b128 v[106:109], v168 offset:4640
	ds_read_b128 v[110:113], v168 offset:64
	ds_read_b128 v[132:135], v168 offset:4672
	ds_read_b128 v[136:139], v168 offset:96
	ds_read_b128 v[140:143], v168 offset:4704
	s_and_b64 vcc, exec, s[20:21]
	s_cbranch_vccnz .Lnb_5
	s_mov_b64 s[98:99], 0xc0000
	v_lshl_add_u64 v[154:155], v[154:155], 0, s[98:99]
	v_lshl_add_u64 v[156:157], v[156:157], 0, s[98:99]
	global_load_dwordx4 v[82:85], v[154:155], off
	global_load_dwordx4 v[86:89], v[156:157], off
	s_and_b64 vcc, exec, s[92:93]
	s_cbranch_vccnz .LBB0_924
	s_mov_b64 s[98:99], 0x60000
	v_lshl_add_u64 v[228:229], v[154:155], 0, s[98:99]
	global_load_dwordx4 v[90:93], v[228:229], off
	v_lshl_add_u64 v[228:229], v[156:157], 0, s[98:99]
	global_load_dwordx4 v[94:97], v[228:229], off
.LBB0_924:
.Lnb_5:
	s_and_b64 vcc, exec, s[18:19]
	s_waitcnt lgkmcnt(7)
	v_mfma_f32_32x32x16_bf16 v[50:65], v[50:53], v[116:119], 0
	s_waitcnt lgkmcnt(6)
	v_mfma_f32_32x32x16_bf16 v[50:65], v[102:105], v[120:123], v[50:65]
	s_waitcnt lgkmcnt(5)
	v_mfma_f32_32x32x16_bf16 v[66:81], v[66:69], v[116:119], 0
	s_waitcnt lgkmcnt(4)
	v_mfma_f32_32x32x16_bf16 v[66:81], v[106:109], v[120:123], v[66:81]
	s_waitcnt lgkmcnt(3)
	v_mfma_f32_32x32x16_bf16 v[50:65], v[110:113], v[124:127], v[50:65]
	s_waitcnt lgkmcnt(2)
	v_mfma_f32_32x32x16_bf16 v[66:81], v[132:135], v[124:127], v[66:81]
	s_waitcnt lgkmcnt(1)
	v_mfma_f32_32x32x16_bf16 v[50:65], v[136:139], v[128:131], v[50:65]
	s_waitcnt lgkmcnt(0)
	v_mfma_f32_32x32x16_bf16 v[66:81], v[140:143], v[128:131], v[66:81]
	s_cbranch_vccnz .LBB0_930
	s_setprio 0

; template <bool HAS_POST, class MaskF>
; __device__ __forceinline__ void attn_run(LAS unsigned char* lds, const bf16* Kg, const bf16* Vg, int pitch, int t0, int t1,
;                                          const bf16x8 (&qr)[4], f32x16& o0, f32x16& o1, f32x16& o2, MaskF& mf, const int wv) {
;     ...
;     for (int ts = t0; ts < t1; ts += 2) {
;         const int cur = ((ts - t0) >> 1) & 1;
;         const bool more = (ts + 2 < t1), more2 = (ts + 3 < t1);
;         if (more) { kp += 2 * tstride; kreg0 = *(const v4u*)kp; vp += 2 * tstride; vreg0 = *(const v4u*)vp;
;             if (more2) { kreg1 = *(const v4u*)(kp + tstride); vreg1 = *(const v4u*)(vp + tstride); } }
.LBB0_960:
	s_add_i32 s1, s3, s96
	s_add_i32 s0, s1, -8
	s_add_i32 s1, s1, -6
	s_cmp_le_i32 s1, s38
	s_cselect_b64 s[20:21], -1, 0
	s_cmp_lt_i32 s0, s23
	s_cselect_b64 s[4:5], -1, 0
	s_cselect_b64 s[94:95], 0, exec
	s_cmp_gt_i32 s1, s38

; #define LAS __attribute__((address_space(3)))
;     __device__ __forceinline__ bool skip(int t) const { const int nb = t >> 2; if (nb >= qb) return 64 * (t & 3) > wq0 + 31; return !__any((int)((sel >> nb) & 1u)); }
; template <bool HAS_POST, class MaskF>
; __device__ __forceinline__ void attn_run(LAS unsigned char* lds, const bf16* Kg, const bf16* Vg, int pitch, int t0, int t1,
;                                          const bf16x8 (&qr)[4], f32x16& o0, f32x16& o1, f32x16& o2, MaskF& mf, const int wv) {
;     ...
;         if (more) { kp += 2 * tstride; kreg0 = *(const v4u*)kp; vp += 2 * tstride; vreg0 = *(const v4u*)vp;
;             if (more2) { kreg1 = *(const v4u*)(kp + tstride); vreg1 = *(const v4u*)(vp + tstride); } }
; #pragma unroll
;         for (int j = 0; j < 2; ++j) {
;             const int t = ts + j;
;             if (t >= t1) break;
;             if (mf.skip(t)) continue;
;             f32x16 p0, p1; const f32x16 zc = {};
;             LAS unsigned char* Kb = lds + (cur * 2 + j) * KBUF + cx.kroff;
;             if (wv < 4) __builtin_amdgcn_s_setprio(1);
; #pragma unroll
;             for (int d0 = 0; d0 < 4; ++d0) {
;                 const bf16x8 a0 = *(const LAS bf16x8*)(Kb + d0 * 32), a1 = *(const LAS bf16x8*)(Kb + 32 * 144 + d0 * 32);
;                 if (d0 == 0) { p0 = __builtin_amdgcn_mfma_f32_32x32x16_bf16(a0, qr[0], zc, 0, 0, 0); p1 = __builtin_amdgcn_mfma_f32_32x32x16_bf16(a1, qr[0], zc, 0, 0, 0); }
;                 else { p0 = __builtin_amdgcn_mfma_f32_32x32x16_bf16(a0, qr[d0], p0, 0, 0, 0); p1 = __builtin_amdgcn_mfma_f32_32x32x16_bf16(a1, qr[d0], p1, 0, 0, 0); }
.LBB0_966:
	s_add_i32 s1, s96, -8
	s_and_b32 s97, s1, 2
	s_mul_i32 s1, s97, 0x2400
	v_add_u32_e32 v54, s1, v207
	ds_read_b128 v[152:155], v54
	ds_read_b128 v[156:159], v54 offset:4608
	ds_read_b128 v[160:163], v54 offset:32
	ds_read_b128 v[164:167], v54 offset:4640
	ds_read_b128 v[168:171], v54 offset:64
	ds_read_b128 v[172:175], v54 offset:4672
	ds_read_b128 v[176:179], v54 offset:96
	ds_read_b128 v[180:183], v54 offset:4704
	s_andn2_b64 vcc, exec, s[20:21]
	s_cbranch_vccnz .Lnb_4
	s_mov_b64 s[98:99], 0xc0000
	v_lshl_add_u64 v[198:199], v[198:199], 0, s[98:99]
	v_lshl_add_u64 v[200:201], v[200:201], 0, s[98:99]
	global_load_dwordx4 v[132:135], v[198:199], off
	global_load_dwordx4 v[136:139], v[200:201], off
	s_and_b64 vcc, exec, s[94:95]
	s_cbranch_vccnz .LBB0_963
	s_mov_b64 s[98:99], 0x60000
	v_lshl_add_u64 v[228:229], v[198:199], 0, s[98:99]
	global_load_dwordx4 v[140:143], v[228:229], off
	v_lshl_add_u64 v[228:229], v[200:201], 0, s[98:99]
	global_load_dwordx4 v[144:147], v[228:229], off
.LBB0_963:
.Lnb_4:
	s_and_b64 vcc, exec, s[18:19]
	s_waitcnt lgkmcnt(7)
	v_mfma_f32_32x32x16_bf16 v[82:97], v[152:155], v[116:119], 0
	s_waitcnt lgkmcnt(6)
	v_mfma_f32_32x32x16_bf16 v[66:81], v[156:159], v[116:119], 0
	s_waitcnt lgkmcnt(5)
	v_mfma_f32_32x32x16_bf16 v[82:97], v[160:163], v[120:123], v[82:97]
	s_waitcnt lgkmcnt(4)
	v_mfma_f32_32x32x16_bf16 v[66:81], v[164:167], v[120:123], v[66:81]
	s_waitcnt lgkmcnt(3)
	v_mfma_f32_32x32x16_bf16 v[82:97], v[168:171], v[124:127], v[82:97]
	s_waitcnt lgkmcnt(2)
	v_mfma_f32_32x32x16_bf16 v[66:81], v[172:175], v[124:127], v[66:81]
	s_waitcnt lgkmcnt(1)
	v_mfma_f32_32x32x16_bf16 v[82:97], v[176:179], v[128:131], v[82:97]
	s_waitcnt lgkmcnt(0)
	v_mfma_f32_32x32x16_bf16 v[66:81], v[180:183], v[128:131], v[66:81]
	s_cbranch_vccnz .LBB0_968
	s_setprio 0

; template <bool HAS_POST, class MaskF>
; __device__ __forceinline__ void attn_run(LAS unsigned char* lds, const bf16* Kg, const bf16* Vg, int pitch, int t0, int t1,
;                                          const bf16x8 (&qr)[4], f32x16& o0, f32x16& o1, f32x16& o2, MaskF& mf, const int wv) {
;     ...
;     for (int ts = t0; ts < t1; ts += 2) {
;         const int cur = ((ts - t0) >> 1) & 1;
;         const bool more = (ts + 2 < t1), more2 = (ts + 3 < t1);
;         if (more) { kp += 2 * tstride; kreg0 = *(const v4u*)kp; vp += 2 * tstride; vreg0 = *(const v4u*)vp;
;             if (more2) { kreg1 = *(const v4u*)(kp + tstride); vreg1 = *(const v4u*)(vp + tstride); } }
.LBB0_1007:
	s_add_i32 s0, s16, -2
	s_cmp_lt_i32 s16, s33
	s_cselect_b64 s[14:15], -1, 0
	s_cmp_ge_i32 s16, s33
	s_cselect_b64 s[12:13], -1, 0
	s_cmp_lt_i32 s0, s2
	s_cselect_b64 s[4:5], -1, 0
	s_cselect_b64 s[6:7], 0, exec
	s_and_b64 vcc, exec, s[12:13]

; template <bool HAS_POST, class MaskF>
; __device__ __forceinline__ void attn_run(LAS unsigned char* lds, const bf16* Kg, const bf16* Vg, int pitch, int t0, int t1,
;                                          const bf16x8 (&qr)[4], f32x16& o0, f32x16& o1, f32x16& o2, MaskF& mf, const int wv) {
;     ...
;     for (int ts = t0; ts < t1; ts += 2) {
;         const int cur = ((ts - t0) >> 1) & 1;
;         const bool more = (ts + 2 < t1), more2 = (ts + 3 < t1);
;         if (more) { kp += 2 * tstride; kreg0 = *(const v4u*)kp; vp += 2 * tstride; vreg0 = *(const v4u*)vp;
;             if (more2) { kreg1 = *(const v4u*)(kp + tstride); vreg1 = *(const v4u*)(vp + tstride); } }
.LBB0_1077:
	s_add_u32 s94, s4, 2
	s_addc_u32 s95, s5, 0
	s_cmp_gt_i32 s94, s39
	s_cselect_b64 s[20:21], -1, 0
	s_cmp_le_i32 s94, s39
	s_cselect_b64 s[96:97], -1, 0
	s_cmp_lt_i32 s4, s27
	s_cselect_b64 s[0:1], -1, 0
	s_cselect_b64 s[92:93], 0, exec
	s_and_b64 vcc, exec, s[20:21]

; template <bool HAS_POST, class MaskF>
; __device__ __forceinline__ void attn_run(LAS unsigned char* lds, const bf16* Kg, const bf16* Vg, int pitch, int t0, int t1,
;                                          const bf16x8 (&qr)[4], f32x16& o0, f32x16& o1, f32x16& o2, MaskF& mf, const int wv) {
;     ...
;     for (int ts = t0; ts < t1; ts += 2) {
;         const int cur = ((ts - t0) >> 1) & 1;
;         const bool more = (ts + 2 < t1), more2 = (ts + 3 < t1);
;         if (more) { kp += 2 * tstride; kreg0 = *(const v4u*)kp; vp += 2 * tstride; vreg0 = *(const v4u*)vp;
;             if (more2) { kreg1 = *(const v4u*)(kp + tstride); vreg1 = *(const v4u*)(vp + tstride); } }
.LBB0_1116:
	s_add_i32 s1, s35, s96
	s_add_i32 s0, s1, -8
	s_add_i32 s1, s1, -6
	s_cmp_le_i32 s1, s39
	s_cselect_b64 s[20:21], -1, 0
	s_cmp_lt_i32 s0, s27
	s_cselect_b64 s[4:5], -1, 0
	s_cselect_b64 s[94:95], 0, exec
	s_cmp_gt_i32 s1, s39

; template <bool HAS_POST, class MaskF>
; __device__ __forceinline__ void attn_run(LAS unsigned char* lds, const bf16* Kg, const bf16* Vg, int pitch, int t0, int t1,
;                                          const bf16x8 (&qr)[4], f32x16& o0, f32x16& o1, f32x16& o2, MaskF& mf, const int wv) {
;     ...
;     for (int ts = t0; ts < t1; ts += 2) {
;         const int cur = ((ts - t0) >> 1) & 1;
;         const bool more = (ts + 2 < t1), more2 = (ts + 3 < t1);
;         if (more) { kp += 2 * tstride; kreg0 = *(const v4u*)kp; vp += 2 * tstride; vreg0 = *(const v4u*)vp;
;             if (more2) { kreg1 = *(const v4u*)(kp + tstride); vreg1 = *(const v4u*)(vp + tstride); } }
.LBB0_1166:
	s_add_i32 s1, s37, -1
	s_add_i32 s58, s37, 1
	s_cmp_lt_u32 s58, s35
	s_cselect_b64 s[4:5], -1, 0
	s_cmp_le_u32 s1, s34
	s_cselect_b64 s[6:7], 0, exec
	s_cmp_ge_u32 s58, s35
	s_cbranch_scc1 .LBB0_1170
	s_mov_b64 s[8:9], 0x100000
	v_lshl_add_u64 v[154:155], v[154:155], 0, s[8:9]
	v_lshl_add_u64 v[156:157], v[156:157], 0, s[8:9]
	global_load_dwordx4 v[96:99], v[154:155], off
	global_load_dwordx4 v[100:103], v[156:157], off
	s_and_b64 vcc, exec, s[6:7]
	s_cbranch_vccnz .LBB0_1169
	s_mov_b64 s[8:9], 0x80000
	v_lshl_add_u64 v[48:49], v[154:155], 0, s[8:9]
	global_load_dwordx4 v[104:107], v[48:49], off
	v_lshl_add_u64 v[48:49], v[156:157], 0, s[8:9]
	global_load_dwordx4 v[108:111], v[48:49], off
